# v94 + one more deferred weight copy per idle S-team workgroup in the UG-GEMM slot (cap 5 to 6)
# baseline (speedup 1.0000x reference)
.LBB0_446:
	v_readlane_b32 s6, v255, 4
	s_xor_b64 s[4:5], s[48:49], -1
	v_readlane_b32 s7, v255, 5
	s_or_b64 s[6:7], s[6:7], s[4:5]
	s_andn2_b64 vcc, exec, s[6:7]
	s_cbranch_vccnz .LBB0_811
	s_cmpk_lt_i32 s2, 0x84
	s_cselect_b64 s[6:7], -1, 0
	s_or_b64 s[4:5], s[6:7], s[4:5]
	s_and_b64 vcc, exec, s[4:5]
	s_cbranch_vccnz .LBB0_488
	s_mov_b64 s[4:5], s[0:1]
	s_load_dwordx2 s[16:17], s[4:5], 0xe0
	s_mov_b32 s28, 6
	v_mov_b32_e32 v3, 0
	s_movk_i32 s30, 0x400
	s_movk_i32 s31, 0x204
	s_waitcnt lgkmcnt(0)
	s_add_u32 s4, s16, 0xa000
	s_addc_u32 s5, s17, 0
	s_add_u32 s6, s16, 0x1800000
	s_addc_u32 s7, s17, 0
	s_add_u32 s8, s16, 0xd00000
	s_addc_u32 s9, s17, 0
	s_add_u32 s10, s16, 0xb00000
	s_addc_u32 s11, s17, 0
	s_add_u32 s12, s16, 0x900000
	s_addc_u32 s13, s17, 0
	s_add_u32 s14, s16, 0x800000
	s_addc_u32 s15, s17, 0
	s_add_u32 s16, s16, 0x200000
	s_addc_u32 s17, s17, 0
	s_add_i32 s29, 0, 0x20180
	v_mov_b32_e32 v1, s29
	s_movk_i32 s34, 0x3ff
	s_movk_i32 s35, 0x700
	s_movk_i32 s36, 0xb00
	s_mov_b32 s37, 0x5040100
	s_mov_b32 s40, 0x7060302
	v_mov_b32_e32 v14, 0x80
	s_branch .LBB0_451
